# e13 plus GEMM phase prologues: the K-tile-1 staging LDS-DMA loads issued together with the K-tile-0 ones, before the first wait and barrier
# baseline (speedup 1.0000x reference)
.LBB0_404:
	s_add_i32 m0, s23, 0x18000
	v_lshl_add_u64 v[2:3], v[2:3], 0, s[66:67]
	global_load_lds_dwordx4 v[2:3], off
	v_lshl_add_u64 v[2:3], v[4:5], 0, s[66:67]
	s_add_i32 m0, s23, 0x1a000
	s_add_i32 s34, s23, 0x8000
	global_load_lds_dwordx4 v[2:3], off
	v_lshl_add_u64 v[2:3], v[10:11], 0, s[66:67]
	s_mov_b32 m0, s34
	s_add_i32 s35, s23, 0xa000
	global_load_lds_dwordx4 v[2:3], off
	v_lshl_add_u64 v[2:3], v[12:13], 0, s[66:67]
	s_mov_b32 m0, s35
	v_lshrrev_b32_e32 v22, 1, v20
	global_load_lds_dwordx4 v[2:3], off
	s_add_i32 m0, s23, 0x1c000
	v_lshl_add_u64 v[2:3], v[6:7], 0, s[66:67]
	global_load_lds_dwordx4 v[2:3], off
	v_lshl_add_u64 v[2:3], v[8:9], 0, s[66:67]
	s_add_i32 m0, s23, 0x1e000
	v_and_b32_e32 v22, 24, v22
	global_load_lds_dwordx4 v[2:3], off
	s_waitcnt vmcnt(8)
	s_barrier
	v_and_b32_e32 v21, 15, v20
	v_readlane_b32 s7, v255, 27
	v_lshlrev_b32_e32 v23, 1, v22
	v_lshlrev_b32_e32 v20, 2, v20
	s_lshl_b32 s5, s5, 5
	s_lshr_b32 s31, s7, 6
	v_lshl_or_b32 v141, s6, 6, v21
	v_lshl_or_b32 v21, v21, 6, v23
	s_lshl_b32 s6, s6, 13
	v_and_b32_e32 v20, 32, v20
	s_and_b32 s5, s5, 0x60
	v_bitop3_b32 v23, v21, s6, v20 bitop3:0xde
	s_lshl_b32 s6, s5, 7
	s_add_i32 s40, s31, -2
	v_add_u32_e32 v2, v19, v17
	s_cmpk_lt_u32 s4, 0x100
	v_add_lshl_u32 v2, v2, v18, 1
	v_mov_b32_e32 v3, v1
	s_waitcnt vmcnt(6)
	s_cselect_b64 s[12:13], -1, 0
	s_ashr_i32 s41, s42, 31
	v_lshl_add_u64 v[136:137], s[50:51], 0, v[2:3]
	v_add_u32_e32 v2, v16, v14
	s_add_u32 s43, s46, s64
	v_add_lshl_u32 v2, v2, v15, 1
	v_bitop3_b32 v144, v21, s6, v20 bitop3:0xde
	s_mov_b32 s9, s51
	s_addc_u32 s55, s47, s65
	v_or_b32_e32 v145, s5, v22
	v_lshl_add_u64 v[138:139], s[50:51], 0, v[2:3]
	s_mov_b32 s64, 0
	v_add_u32_e32 v146, 0, v23
	s_barrier
	s_branch .LBB0_407

.LBB0_434:
	s_add_i32 m0, s15, 0x18000
	v_lshl_add_u64 v[2:3], v[2:3], 0, s[66:67]
	global_load_lds_dwordx4 v[2:3], off
	v_lshl_add_u64 v[2:3], v[4:5], 0, s[66:67]
	s_add_i32 m0, s15, 0x1a000
	s_add_i32 s43, s15, 0x8000
	global_load_lds_dwordx4 v[2:3], off
	v_lshl_add_u64 v[2:3], v[10:11], 0, s[66:67]
	s_mov_b32 m0, s43
	s_add_i32 s55, s15, 0xa000
	global_load_lds_dwordx4 v[2:3], off
	v_lshl_add_u64 v[2:3], v[12:13], 0, s[66:67]
	s_mov_b32 m0, s55
	v_bfe_u32 v249, v20, 4, 2
	global_load_lds_dwordx4 v[2:3], off
	s_add_i32 m0, s15, 0x1c000
	v_lshl_add_u64 v[2:3], v[6:7], 0, s[66:67]
	global_load_lds_dwordx4 v[2:3], off
	v_lshl_add_u64 v[2:3], v[8:9], 0, s[66:67]
	s_add_i32 m0, s15, 0x1e000
	v_and_b32_e32 v243, 15, v20
	global_load_lds_dwordx4 v[2:3], off
	s_waitcnt vmcnt(8)
	s_barrier
	v_readlane_b32 s7, v255, 27
	v_lshlrev_b32_e32 v21, 4, v249
	v_lshlrev_b32_e32 v20, 2, v20
	s_and_b32 s6, s6, 3
	s_lshr_b32 s23, s7, 6
	v_lshl_or_b32 v21, v243, 6, v21
	s_lshl_b32 s7, s5, 13
	v_and_b32_e32 v20, 32, v20
	s_lshl_b32 s30, s5, 6
	v_bitop3_b32 v22, v21, s7, v20 bitop3:0xde
	s_lshl_b32 s31, s6, 5
	s_lshl_b32 s7, s6, 12
	s_add_i32 s64, s23, -2
	s_cmpk_lt_u32 s4, 0x100
	s_cselect_b64 s[34:35], -1, 0
	s_lshl_b32 s4, s5, 10
	s_lshl_b32 s5, s5, 7
	v_add_u32_e32 v2, v16, v14
	s_or_b32 s65, s31, s5
	s_lshl_b32 s5, s6, 2
	v_add_lshl_u32 v2, v2, v15, 1
	v_mov_b32_e32 v3, v1
	s_waitcnt vmcnt(6)
	s_add_i32 s5, s5, 0
	v_lshl_add_u64 v[200:201], s[50:51], 0, v[2:3]
	v_add_u32_e32 v2, v19, v17
	s_add_i32 s74, s5, s4
	v_add_lshl_u32 v2, v2, v18, 1
	v_bitop3_b32 v251, v21, s7, v20 bitop3:0xde
	s_ashr_i32 s68, s42, 31
	s_ashr_i32 s69, s90, 31
	s_add_i32 s74, s74, 0x20400
	v_lshl_add_u64 v[202:203], s[50:51], 0, v[2:3]
	s_mov_b32 s75, 0
	v_add_u32_e32 v252, 0, v22
	s_barrier
	s_branch .LBB0_444

.LBB0_505:
	s_add_i32 m0, s19, 0x18000
	v_lshl_add_u64 v[2:3], v[2:3], 0, s[66:67]
	global_load_lds_dwordx4 v[2:3], off
	v_lshl_add_u64 v[2:3], v[4:5], 0, s[66:67]
	s_add_i32 m0, s19, 0x1a000
	s_add_i32 s64, s19, 0x8000
	global_load_lds_dwordx4 v[2:3], off
	v_lshl_add_u64 v[2:3], v[10:11], 0, s[66:67]
	s_mov_b32 m0, s64
	s_add_i32 s65, s19, 0xa000
	global_load_lds_dwordx4 v[2:3], off
	v_lshl_add_u64 v[2:3], v[12:13], 0, s[66:67]
	s_mov_b32 m0, s65
	v_bfe_u32 v238, v20, 4, 2
	global_load_lds_dwordx4 v[2:3], off
	s_add_i32 m0, s19, 0x1c000
	v_lshl_add_u64 v[2:3], v[6:7], 0, s[66:67]
	global_load_lds_dwordx4 v[2:3], off
	v_lshl_add_u64 v[2:3], v[8:9], 0, s[66:67]
	s_add_i32 m0, s19, 0x1e000
	v_and_b32_e32 v239, 15, v20
	global_load_lds_dwordx4 v[2:3], off
	s_waitcnt vmcnt(8)
	s_barrier
	v_readlane_b32 s7, v255, 27
	v_lshlrev_b32_e32 v21, 4, v238
	v_lshlrev_b32_e32 v20, 2, v20
	s_and_b32 s6, s6, 3
	s_lshr_b32 s41, s7, 6
	v_lshl_or_b32 v21, v239, 6, v21
	s_lshl_b32 s7, s5, 13
	v_and_b32_e32 v20, 32, v20
	s_lshl_b32 s43, s5, 6
	v_bitop3_b32 v22, v21, s7, v20 bitop3:0xde
	s_lshl_b32 s55, s6, 5
	s_lshl_b32 s7, s6, 12
	s_add_i32 s68, s41, -2
	s_cmpk_lt_u32 s4, 0x100
	s_cselect_b64 s[30:31], -1, 0
	s_lshl_b32 s4, s5, 10
	s_lshl_b32 s5, s5, 7
	v_add_u32_e32 v2, v16, v14
	s_or_b32 s69, s55, s5
	s_lshl_b32 s5, s6, 2
	v_add_lshl_u32 v2, v2, v15, 1
	v_mov_b32_e32 v3, v1
	s_waitcnt vmcnt(6)
	s_add_i32 s5, s5, 0
	v_lshl_add_u64 v[196:197], s[50:51], 0, v[2:3]
	v_add_u32_e32 v2, v19, v17
	s_add_i32 s78, s5, s4
	v_add_lshl_u32 v2, v2, v18, 1
	v_bitop3_b32 v240, v21, s7, v20 bitop3:0xde
	s_ashr_i32 s74, s42, 31
	s_ashr_i32 s75, s90, 31
	s_add_i32 s78, s78, 0x20400
	v_lshl_add_u64 v[198:199], s[50:51], 0, v[2:3]
	s_mov_b32 s79, 0
	v_add_u32_e32 v241, 0, v22
	s_barrier
	s_branch .LBB0_508

.LBB0_578:
	s_add_i32 m0, s19, 0x18000
	v_lshl_add_u64 v[2:3], v[2:3], 0, s[66:67]
	global_load_lds_dwordx4 v[2:3], off
	v_lshl_add_u64 v[2:3], v[4:5], 0, s[66:67]
	s_add_i32 m0, s19, 0x1a000
	s_add_i32 s68, s19, 0x8000
	global_load_lds_dwordx4 v[2:3], off
	v_lshl_add_u64 v[2:3], v[10:11], 0, s[66:67]
	s_mov_b32 m0, s68
	s_add_i32 s69, s19, 0xa000
	global_load_lds_dwordx4 v[2:3], off
	v_lshl_add_u64 v[2:3], v[12:13], 0, s[66:67]
	s_mov_b32 m0, s69
	v_bfe_u32 v188, v20, 4, 2
	global_load_lds_dwordx4 v[2:3], off
	s_add_i32 m0, s19, 0x1c000
	v_lshl_add_u64 v[2:3], v[6:7], 0, s[66:67]
	global_load_lds_dwordx4 v[2:3], off
	v_lshl_add_u64 v[2:3], v[8:9], 0, s[66:67]
	s_add_i32 m0, s19, 0x1e000
	v_and_b32_e32 v189, 15, v20
	global_load_lds_dwordx4 v[2:3], off
	s_waitcnt vmcnt(8)
	s_barrier
	v_readlane_b32 s7, v255, 27
	v_lshlrev_b32_e32 v21, 4, v188
	v_lshlrev_b32_e32 v20, 2, v20
	s_and_b32 s6, s6, 3
	s_lshr_b32 s41, s7, 6
	v_lshl_or_b32 v21, v189, 6, v21
	s_lshl_b32 s7, s5, 13
	v_and_b32_e32 v20, 32, v20
	s_lshl_b32 s43, s5, 6
	v_bitop3_b32 v22, v21, s7, v20 bitop3:0xde
	s_lshl_b32 s55, s6, 5
	s_lshl_b32 s7, s6, 12
	s_add_i32 s74, s41, -2
	s_cmpk_lt_u32 s4, 0x100
	s_cselect_b64 s[30:31], -1, 0
	s_lshl_b32 s4, s5, 2
	s_or_b32 s4, s4, s6
	s_lshl_b32 s5, s5, 10
	s_lshl_b32 s75, s4, 5
	s_cmp_eq_u32 s4, 0
	v_add_u32_e32 v2, v16, v14
	s_cselect_b64 s[34:35], -1, 0
	s_lshl_b32 s4, s6, 2
	v_add_lshl_u32 v2, v2, v15, 1
	v_mov_b32_e32 v3, v1
	s_waitcnt vmcnt(6)
	s_add_i32 s4, s4, 0
	v_lshl_add_u64 v[152:153], s[50:51], 0, v[2:3]
	v_add_u32_e32 v2, v19, v17
	s_add_i32 s86, s4, s5
	v_add_lshl_u32 v2, v2, v18, 1
	v_bitop3_b32 v190, v21, s7, v20 bitop3:0xde
	s_mov_b32 s78, 0
	s_ashr_i32 s79, s42, 31
	s_ashr_i32 s83, s90, 31
	s_add_i32 s86, s86, 0x20400
	v_lshl_add_u64 v[154:155], s[50:51], 0, v[2:3]
	v_add_u32_e32 v191, 0, v22
	s_barrier
	s_branch .LBB0_581

.LBB0_637:
	s_add_i32 m0, s28, 0x18000
	v_lshl_add_u64 v[2:3], v[2:3], 0, s[66:67]
	global_load_lds_dwordx4 v[2:3], off
	v_lshl_add_u64 v[2:3], v[4:5], 0, s[66:67]
	s_add_i32 m0, s28, 0x1a000
	s_add_i32 s39, s28, 0x8000
	global_load_lds_dwordx4 v[2:3], off
	v_lshl_add_u64 v[2:3], v[10:11], 0, s[66:67]
	s_mov_b32 m0, s39
	s_add_i32 s40, s28, 0xa000
	global_load_lds_dwordx4 v[2:3], off
	v_lshl_add_u64 v[2:3], v[12:13], 0, s[66:67]
	s_mov_b32 m0, s40
	v_lshrrev_b32_e32 v22, 1, v20
	global_load_lds_dwordx4 v[2:3], off
	s_add_i32 m0, s28, 0x1c000
	v_lshl_add_u64 v[2:3], v[6:7], 0, s[66:67]
	global_load_lds_dwordx4 v[2:3], off
	v_lshl_add_u64 v[2:3], v[8:9], 0, s[66:67]
	s_add_i32 m0, s28, 0x1e000
	v_and_b32_e32 v22, 24, v22
	global_load_lds_dwordx4 v[2:3], off
	s_waitcnt vmcnt(8)
	s_barrier
	s_sext_i32_i16 s25, s4
	v_and_b32_e32 v21, 15, v20
	v_readlane_b32 s4, v255, 27
	v_lshlrev_b32_e32 v23, 1, v22
	v_lshlrev_b32_e32 v20, 2, v20
	s_lshr_b32 s38, s4, 6
	v_lshl_or_b32 v238, s7, 6, v21
	v_lshl_or_b32 v21, v21, 6, v23
	s_lshl_b32 s4, s7, 13
	v_and_b32_e32 v20, 32, v20
	v_bitop3_b32 v23, v21, s4, v20 bitop3:0xde
	s_lshl_b32 s4, s6, 5
	v_add_u32_e32 v2, v19, v17
	s_and_b32 s4, s4, 0x60
	v_add_lshl_u32 v2, v2, v18, 1
	v_mov_b32_e32 v3, v1
	s_lshl_b32 s6, s4, 7
	s_waitcnt vmcnt(6)
	s_add_i32 s41, s38, -2
	v_lshl_add_u64 v[196:197], s[50:51], 0, v[2:3]
	v_add_u32_e32 v2, v16, v14
	s_cmpk_lt_u32 s5, 0x100
	v_add_lshl_u32 v2, v2, v15, 1
	v_bitop3_b32 v239, v21, s6, v20 bitop3:0xde
	s_cselect_b64 s[30:31], -1, 0
	s_ashr_i32 s43, s42, 31
	s_mov_b32 s9, s51
	v_or_b32_e32 v240, s4, v22
	v_lshl_add_u64 v[198:199], s[50:51], 0, v[2:3]
	s_mov_b32 s52, 0
	v_add_u32_e32 v241, 0, v23
	s_barrier
	s_branch .LBB0_640

.LBB0_659:
	s_add_i32 m0, s26, 0x18000
	v_lshl_add_u64 v[10:11], v[10:11], 0, s[66:67]
	global_load_lds_dwordx4 v[10:11], off
	v_lshl_add_u64 v[6:7], v[6:7], 0, s[66:67]
	s_add_i32 m0, s26, 0x1a000
	s_add_i32 s30, s26, 0x8000
	global_load_lds_dwordx4 v[6:7], off
	v_lshl_add_u64 v[6:7], v[8:9], 0, s[66:67]
	s_mov_b32 m0, s30
	s_add_i32 s31, s26, 0xa000
	global_load_lds_dwordx4 v[6:7], off
	v_lshl_add_u64 v[6:7], v[12:13], 0, s[66:67]
	s_mov_b32 m0, s31
	v_lshl_add_u64 v[4:5], v[4:5], 0, s[66:67]
	global_load_lds_dwordx4 v[6:7], off
	s_add_i32 m0, s26, 0x1c000
	v_lshl_add_u64 v[2:3], v[2:3], 0, s[66:67]
	global_load_lds_dwordx4 v[4:5], off
	s_add_i32 m0, s26, 0x1e000
	s_sext_i32_i16 s41, s4
	global_load_lds_dwordx4 v[2:3], off
	s_waitcnt vmcnt(8)
	s_barrier
	v_lshrrev_b32_e32 v3, 1, v14
	v_and_b32_e32 v3, 24, v3
	v_and_b32_e32 v2, 15, v14
	v_lshlrev_b32_e32 v4, 1, v3
	v_readlane_b32 s4, v255, 27
	v_lshl_or_b32 v142, s7, 6, v2
	v_lshl_or_b32 v2, v2, 6, v4
	v_lshlrev_b32_e32 v4, 2, v14
	s_lshr_b32 s34, s4, 6
	s_lshl_b32 s4, s7, 13
	v_and_b32_e32 v4, 32, v4
	v_bitop3_b32 v5, v2, s4, v4 bitop3:0xde
	s_lshl_b32 s4, s6, 5
	s_and_b32 s4, s4, 0x60
	s_lshl_b32 s6, s4, 7
	v_bitop3_b32 v143, v2, s6, v4 bitop3:0xde
	v_add_u32_e32 v2, v20, v18
	v_or_b32_e32 v144, s4, v3
	v_add_lshl_u32 v2, v2, v19, 1
	v_mov_b32_e32 v3, v1
	s_waitcnt vmcnt(6)
	s_add_i32 s35, s34, -2
	v_lshl_add_u64 v[136:137], s[50:51], 0, v[2:3]
	v_add_u32_e32 v2, v17, v15
	s_cmpk_lt_u32 s5, 0x100
	v_add_lshl_u32 v2, v2, v16, 1
	s_cselect_b64 s[20:21], -1, 0
	s_ashr_i32 s36, s42, 31
	s_mov_b32 s9, s51
	v_lshl_add_u64 v[138:139], s[50:51], 0, v[2:3]
	s_mov_b32 s37, 0
	v_add_u32_e32 v145, 0, v5
	s_barrier
	s_branch .LBB0_662
